# always-full barriers (S5 seams, out-proj->gate/up): the first workgroup of each XCD to arrive starts an L2 writeback early, so the leader's final writeback has less dirty data
# baseline (speedup 1.0000x reference)
.LBB0_180:
	s_or_b64 exec, exec, s[12:13]
	v_cvt_f32_u32_e32 v5, v3
	s_waitcnt vmcnt(0)
	v_readfirstlane_b32 s2, v4
	v_sub_u32_e32 v4, 0, v3
	v_rcp_iflag_f32_e32 v5, v5
	v_add_u32_e32 v6, s2, v0
	v_mul_f32_e32 v5, 0x4f7ffffe, v5
	v_cvt_u32_f32_e32 v5, v5
	v_mul_lo_u32 v0, v4, v5
	v_mul_hi_u32 v0, v5, v0
	v_add_u32_e32 v0, v5, v0
	v_mul_hi_u32 v0, v6, v0
	v_mul_lo_u32 v4, v0, v3
	v_sub_u32_e32 v4, v6, v4
	v_add_u32_e32 v5, 1, v0
	v_cmp_ge_u32_e32 vcc, v4, v3
	s_nop 1
	v_cndmask_b32_e32 v0, v0, v5, vcc
	v_sub_u32_e32 v5, v4, v3
	v_cndmask_b32_e32 v4, v4, v5, vcc
	v_add_u32_e32 v5, 1, v0
	v_cmp_ge_u32_e32 vcc, v4, v3
	v_add_u32_e32 v4, 1, v6
	s_nop 0
	v_cndmask_b32_e32 v0, v0, v5, vcc
	v_mul_lo_u32 v5, v3, v0
	v_add_u32_e32 v3, v5, v3
	v_cmp_ne_u32_e32 vcc, v4, v3
	s_and_saveexec_b64 s[2:3], vcc
	s_xor_b64 s[10:11], exec, s[2:3]
	s_cbranch_execz .LBB0_203
	v_cmp_eq_u32_e32 vcc, v6, v5
	s_cbranch_vccz .Lnofirst_233
	buffer_wbl2 sc1
.Lnofirst_233:
	s_add_u32 s12, s8, 0x2400
	s_addc_u32 s13, s9, 0
	s_mov_b32 s2, 0x1000000
	s_mov_b64 s[14:15], 0
	s_branch .LBB0_191
